# mLSTM chunk output: permlane32_swap pairs, 2x dwordx4 stores per lane instead of 4x dwordx2
# speedup vs baseline: 1.0025x; 1.0025x over previous
; DI unsigned pack2(float a, float b) { f32x2_t v = {a, b}; bf16x2_t r = __builtin_convertvector(v, bf16x2_t); return __builtin_bit_cast(unsigned, r); }
; DI void mlstm_job(const PX& p, int l, int job, unsigned char* smem) {
;     ...
;       if (w < 6) {
; #pragma unroll
;         for (int ti = 0; ti < 2; ti++) {
;           const int tl = ti * 32 + lr;
;           const float dn = fmaxf(fabsf(denA[tl]), emtA[par * 64 + tl]);
;           const float inv = 1.f / dn;
;           const int pos = c * 64 + tl;
;           const int t = dir ? Lseg - 1 - pos : pos;
;           bfu* dst = H + (size_t)(tokbase + t) * 768 + h * 192 + 32 * w + 4 * lh;
; #pragma unroll
;           for (int g4 = 0; g4 < 4; g4++) {
;             uint2 o;
;             o.x = pack2(num[ti][4 * g4] * inv, num[ti][4 * g4 + 1] * inv);
;             o.y = pack2(num[ti][4 * g4 + 2] * inv, num[ti][4 * g4 + 3] * inv);
;             *(uint2*)(dst + 8 * g4) = o;
;           }
;         }
;       }
.LBB0_462:
	s_or_b64 exec, exec, s[62:63]
	s_barrier
	s_mov_b64 s[62:63], exec
	v_readlane_b32 s0, v255, 27
	v_readlane_b32 s1, v255, 28
	s_and_b64 s[0:1], s[62:63], s[0:1]
	s_mov_b64 exec, s[0:1]
	s_cbranch_execz .LBB0_448
	v_add_u32_e32 v2, s27, v251
	ds_read_b32 v0, v189
	ds_read2_b32 v[2:3], v2 offset1:32
	s_waitcnt lgkmcnt(1)
	v_max_f32_e64 v0, |v0|, |v0|
	s_waitcnt lgkmcnt(0)
	v_max_f32_e32 v2, v2, v2
	v_max_f32_e32 v0, v0, v2
	v_div_scale_f32 v2, s[0:1], v0, v0, 1.0
	v_rcp_f32_e32 v4, v2
	s_nop 0
	v_fma_f32 v5, -v2, v4, 1.0
	v_fmac_f32_e32 v4, v5, v4
	v_div_scale_f32 v5, vcc, 1.0, v0, 1.0
	v_mul_f32_e32 v6, v5, v4
	v_fma_f32 v7, -v2, v6, v5
	v_fmac_f32_e32 v6, v7, v4
	v_fma_f32 v2, -v2, v6, v5
	v_div_fmas_f32 v2, v2, v4, v6
	v_div_fixup_f32 v0, v2, v0, 1.0
	v_or_b32_e32 v2, s26, v176
	v_xad_u32 v4, v2, -1, s69
	v_cndmask_b32_e64 v2, v4, v2, s[4:5]
	v_add_u32_e32 v2, s61, v2
	v_mad_i64_i32 v[4:5], s[0:1], v2, s81, v[166:167]
	v_and_b32_e32 v14, 32, v211
	v_lshrrev_b32_e32 v14, 2, v14
	v_mov_b32_e32 v15, 0
	v_lshl_add_u64 v[4:5], v[4:5], 0, v[14:15]
	v_pk_mul_f32 v[6:7], v[128:129], v[0:1] op_sel_hi:[1,0]
	v_pk_mul_f32 v[8:9], v[130:131], v[0:1] op_sel_hi:[1,0]
	v_pk_mul_f32 v[10:11], v[132:133], v[0:1] op_sel_hi:[1,0]
	v_pk_mul_f32 v[12:13], v[134:135], v[0:1] op_sel_hi:[1,0]
	s_nop 0
	v_cvt_pk_bf16_f32 v6, v6, v7
	v_cvt_pk_bf16_f32 v7, v8, v9
	v_cvt_pk_bf16_f32 v8, v10, v11
	v_cvt_pk_bf16_f32 v9, v12, v13
	s_nop 1
	v_permlane32_swap_b32_e32 v6, v8
	v_permlane32_swap_b32_e32 v7, v9
	global_store_dwordx4 v[4:5], v[6:9], off
	s_nop 1
	v_pk_mul_f32 v[6:7], v[136:137], v[0:1] op_sel_hi:[1,0]
	v_pk_mul_f32 v[8:9], v[138:139], v[0:1] op_sel_hi:[1,0]
	v_pk_mul_f32 v[10:11], v[140:141], v[0:1] op_sel_hi:[1,0]
	v_pk_mul_f32 v[12:13], v[142:143], v[0:1] op_sel_hi:[1,0]
	s_nop 0
	v_cvt_pk_bf16_f32 v6, v6, v7
	v_cvt_pk_bf16_f32 v7, v8, v9
	v_cvt_pk_bf16_f32 v8, v10, v11
	v_cvt_pk_bf16_f32 v9, v12, v13
	s_nop 1
	v_permlane32_swap_b32_e32 v6, v8
	v_permlane32_swap_b32_e32 v7, v9
	global_store_dwordx4 v[4:5], v[6:9], off offset:32
	s_nop 1
	ds_read_b32 v0, v250
	v_max_f32_e32 v2, v3, v3
	s_waitcnt lgkmcnt(0)
	v_max_f32_e64 v0, |v0|, |v0|
	v_max_f32_e32 v0, v0, v2
	v_div_scale_f32 v2, s[0:1], v0, v0, 1.0
	v_rcp_f32_e32 v4, v2
	s_nop 0
	v_fma_f32 v5, -v2, v4, 1.0
	v_fmac_f32_e32 v4, v5, v4
	v_div_scale_f32 v5, vcc, 1.0, v0, 1.0
	v_mul_f32_e32 v6, v5, v4
	v_fma_f32 v7, -v2, v6, v5
	v_fmac_f32_e32 v6, v7, v4
	v_fma_f32 v2, -v2, v6, v5
	v_div_fmas_f32 v2, v2, v4, v6
	v_div_fixup_f32 v0, v2, v0, 1.0
	v_or_b32_e32 v2, s26, v249
	v_xad_u32 v4, v2, -1, s69
	v_cndmask_b32_e64 v2, v4, v2, s[4:5]
	v_add_u32_e32 v2, s61, v2
	v_mad_i64_i32 v[4:5], s[0:1], v2, s81, v[166:167]
	v_and_b32_e32 v14, 32, v211
	v_lshrrev_b32_e32 v14, 2, v14
	v_mov_b32_e32 v15, 0
	v_lshl_add_u64 v[4:5], v[4:5], 0, v[14:15]
	v_pk_mul_f32 v[6:7], v[112:113], v[0:1] op_sel_hi:[1,0]
	v_pk_mul_f32 v[8:9], v[114:115], v[0:1] op_sel_hi:[1,0]
	v_pk_mul_f32 v[10:11], v[116:117], v[0:1] op_sel_hi:[1,0]
	v_pk_mul_f32 v[12:13], v[118:119], v[0:1] op_sel_hi:[1,0]
	s_nop 0
	v_cvt_pk_bf16_f32 v6, v6, v7
	v_cvt_pk_bf16_f32 v7, v8, v9
	v_cvt_pk_bf16_f32 v8, v10, v11
	v_cvt_pk_bf16_f32 v9, v12, v13
	s_nop 1
	v_permlane32_swap_b32_e32 v6, v8
	v_permlane32_swap_b32_e32 v7, v9
	global_store_dwordx4 v[4:5], v[6:9], off
	s_nop 1
	v_pk_mul_f32 v[6:7], v[120:121], v[0:1] op_sel_hi:[1,0]
	v_pk_mul_f32 v[8:9], v[122:123], v[0:1] op_sel_hi:[1,0]
	v_pk_mul_f32 v[10:11], v[124:125], v[0:1] op_sel_hi:[1,0]
	v_pk_mul_f32 v[12:13], v[126:127], v[0:1] op_sel_hi:[1,0]
	s_nop 0
	v_cvt_pk_bf16_f32 v6, v6, v7
	v_cvt_pk_bf16_f32 v7, v8, v9
	v_cvt_pk_bf16_f32 v8, v10, v11
	v_cvt_pk_bf16_f32 v9, v12, v13
	s_nop 1
	v_permlane32_swap_b32_e32 v6, v8
	v_permlane32_swap_b32_e32 v7, v9
	global_store_dwordx4 v[4:5], v[6:9], off offset:32
	s_nop 1
	s_branch .LBB0_448
